# grid barrier: XCD leaders wait on the top-level arrive counter itself instead of the separate generation word (one fewer hop)
# speedup vs baseline: 1.0087x; 1.0087x over previous
; __device__ __forceinline__ unsigned xb_ld(unsigned* p) { return __hip_atomic_load(p, __ATOMIC_RELAXED, __HIP_MEMORY_SCOPE_AGENT); }
; __device__ __forceinline__ unsigned xb_add(unsigned* p, unsigned v) { return __hip_atomic_fetch_add(p, v, __ATOMIC_RELAXED, __HIP_MEMORY_SCOPE_AGENT); }
; #define XB_SPIN(cond, bar) do { unsigned _sp = 0; while (cond) { __builtin_amdgcn_s_sleep(1); \
;     if ((++_sp & 255u) == 0u) { if (xb_ld(&(bar)[XB_TMO])) break; if (_sp > XB_SPIN_CAP) { atomicAdd(&(bar)[XB_TMO], 1u); break; } } } } while (0)
; __device__ __forceinline__ void xcd_barrier(const XcdBarrier& b) {
;     ...
;       const unsigned og = xb_add(&bar[XB_TOP], 1u);
;       const unsigned tg = og / nx;
;       if (og + 1u == (tg + 1u) * nx) xb_add(&bar[XB_TOPGEN], 1u);
;       else XB_SPIN(xb_ld(&bar[XB_TOPGEN]) == tg, bar);
.LBB0_1362:
	s_or_b64 exec, exec, s[4:5]
	s_waitcnt vmcnt(0)
	v_readfirstlane_b32 s2, v2
	v_cvt_f32_u32_e32 v2, v0
	v_sub_u32_e32 v3, 0, v0
	v_add_u32_e32 v1, s2, v1
	v_readlane_b32 s0, v253, 43
	v_rcp_iflag_f32_e32 v2, v2
	v_readlane_b32 s1, v253, 44
	s_mov_b64 s[4:5], -1
	v_mul_f32_e32 v2, 0x4f7ffffe, v2
	v_cvt_u32_f32_e32 v2, v2
	v_mul_lo_u32 v3, v3, v2
	v_mul_hi_u32 v3, v2, v3
	v_add_u32_e32 v2, v2, v3
	v_mul_hi_u32 v2, v1, v2
	v_mul_lo_u32 v3, v2, v0
	v_sub_u32_e32 v3, v1, v3
	v_cmp_ge_u32_e32 vcc, v3, v0
	v_add_u32_e32 v4, 1, v2
	v_add_u32_e32 v1, 1, v1
	v_cndmask_b32_e32 v2, v2, v4, vcc
	v_sub_u32_e32 v4, v3, v0
	v_cndmask_b32_e32 v3, v3, v4, vcc
	v_cmp_ge_u32_e32 vcc, v3, v0
	v_add_u32_e32 v3, 1, v2
	s_nop 0
	v_cndmask_b32_e32 v2, v2, v3, vcc
	v_mul_lo_u32 v3, v0, v2
	v_add_u32_e32 v0, v3, v0
	v_cmp_ne_u32_e32 vcc, v1, v0
	v_mov_b32_e32 v4, v0
	v_mov_b64_e32 v[0:1], s[0:1]
	s_and_saveexec_b64 s[2:3], vcc
	s_cbranch_execz .LBB0_1374
	v_readlane_b32 s0, v253, 41
	v_readlane_b32 s1, v253, 42
	s_mov_b64 s[12:13], 0
	s_nop 3
	global_load_dword v0, v149, s[0:1] sc1
	s_waitcnt vmcnt(0)
	v_cmp_lt_u32_e32 vcc, v0, v4
	s_and_saveexec_b64 s[4:5], vcc
	s_cbranch_execz .LBB0_1373
	s_mov_b32 s10, 1
	s_branch .LBB0_1366

; __device__ __forceinline__ unsigned xb_ld(unsigned* p) { return __hip_atomic_load(p, __ATOMIC_RELAXED, __HIP_MEMORY_SCOPE_AGENT); }
; __device__ __forceinline__ unsigned xb_add(unsigned* p, unsigned v) { return __hip_atomic_fetch_add(p, v, __ATOMIC_RELAXED, __HIP_MEMORY_SCOPE_AGENT); }
; #define XB_SPIN(cond, bar) do { unsigned _sp = 0; while (cond) { __builtin_amdgcn_s_sleep(1); \
;     if ((++_sp & 255u) == 0u) { if (xb_ld(&(bar)[XB_TMO])) break; if (_sp > XB_SPIN_CAP) { atomicAdd(&(bar)[XB_TMO], 1u); break; } } } } while (0)
; __device__ __forceinline__ void xcd_barrier(const XcdBarrier& b) {
;     ...
;       const unsigned og = xb_add(&bar[XB_TOP], 1u);
;       const unsigned tg = og / nx;
;       if (og + 1u == (tg + 1u) * nx) xb_add(&bar[XB_TOPGEN], 1u);
;       else XB_SPIN(xb_ld(&bar[XB_TOPGEN]) == tg, bar);
.LBB0_1368:
	v_readlane_b32 s0, v253, 41
	v_readlane_b32 s1, v253, 42
	s_add_i32 s10, s10, 1
	s_mov_b64 s[36:37], -1
	s_nop 2
	global_load_dword v0, v149, s[0:1] sc1
	s_waitcnt vmcnt(0)
	v_cmp_ge_u32_e32 vcc, v0, v4
	s_orn2_b64 s[30:31], vcc, exec
	s_branch .LBB0_1365
